# mixer queue: MoBA units and conv items request the next ticket a few us before finishing; dequeue consumes it when present
# baseline (speedup 1.0000x reference)
; __global__ void __launch_bounds__(NTHREADS, 2) fwd_megakernel(Params p_) {
;     ...
;             for (;;) {
;                 if (tid == 0) *qslot = __hip_atomic_fetch_add(qctr, 1u, __ATOMIC_RELAXED, __HIP_MEMORY_SCOPE_AGENT);
;                 __syncthreads();
;                 const int idx = __builtin_amdgcn_readfirstlane((int)*qslot);
;                 __syncthreads();
;                 if (idx >= total) break;
.LBB0_322:
	s_and_saveexec_b64 s[0:1], s[18:19]
	s_cbranch_execz .LBB0_326
	s_cmp_lg_u32 s98, 1
	s_cbranch_scc1 .Lq_nopref
	s_waitcnt vmcnt(0)
	v_mov_b32_e32 v2, v237
	v_mov_b32_e32 v0, 0
	s_branch .Lq_join
.Lq_nopref:
	s_mov_b64 s[8:9], exec
	v_mbcnt_lo_u32_b32 v0, s8, 0
	v_mbcnt_hi_u32_b32 v0, s9, v0
	v_cmp_eq_u32_e32 vcc, 0, v0
	s_and_saveexec_b64 s[2:3], vcc
	s_cbranch_execz .LBB0_325
	s_bcnt1_i32_b64 s4, s[8:9]
	v_mov_b32_e32 v2, s4
	v_readlane_b32 s4, v255, 18
	v_readlane_b32 s5, v255, 19
	s_nop 4
	global_atomic_add v2, v1, v2, s[4:5] sc0

; #define LAS __attribute__((address_space(3)))
; __device__ __forceinline__ void sb_unit(LAS unsigned char* lds, const bf16* PROJ, bf16* MIX, int b, int h, int jq, int tid) {
;     const int lane = tid & 63, wid = __builtin_amdgcn_readfirstlane(tid >> 6), r32 = lane & 31, hi = lane >> 5;
;     const size_t rowbase = (size_t)b * SEQ; const int q0 = 256 * jq;
;     const bf16* Kg = PROJ + rowbase * NPROJ + 1536 + h * 64; const bf16* Vg = PROJ + rowbase * NPROJ + 2048 + h * 64;
;     const bf16* Qp = PROJ + (rowbase + q0 + 32 * wid + r32) * NPROJ + 1024 + h * 64;
;     bf16x8 qr[4];
; #pragma unroll
;     for (int d0 = 0; d0 < 4; ++d0) qr[d0] = *(const bf16x8*)(Qp + 16 * d0 + 8 * hi);
;     const int NT = 4 * jq + 4;
;     u32x4 kr, vr, kr1, vr1; tile_load(Kg, Vg, 64 * (NT - 1), tid, kr, vr); tile_load(Kg, Vg, 64 * (NT - 2), tid, kr1, vr1);
;     tile_store(lds, 0, tid, kr, vr); tile_store(lds, TILEB, tid, kr1, vr1);
;     __syncthreads();
; __global__ void __launch_bounds__(NTHREADS, 2) fwd_megakernel(Params p_) {
;     ...
;             for (;;) {
;                 if (tid == 0) *qslot = __hip_atomic_fetch_add(qctr, 1u, __ATOMIC_RELAXED, __HIP_MEMORY_SCOPE_AGENT);
;                 __syncthreads();
;                 const int idx = __builtin_amdgcn_readfirstlane((int)*qslot);
;                 __syncthreads();
;                 if (idx >= total) break;
;                 int tq_; asm volatile("v_mov_b32 %0, %1" : "=v"(tq_) : "v"(tid));
;                 const int tq = tq_;
;                 if (even) {
;                     if (idx < 512) { const int j = 7 - (idx >> 6), bh = idx & 63; mx::moba_unit(lds, PROJ, MIX, bh >> 3, bh & 7, j, tq); }
;                     else mx::conv_item(lds, PROJ, MIX, p->conv_w + (size_t)li * 31 * 512, p->conv_b + li * 512, p->conv_ln_g + li * 512, p->conv_ln_b + li * 512, idx - 512, tq);
;                 } else {
;                     if (idx < 128) mx::sgu_item(lds, PROJ, MIX, p->sgu_ln_g + li * 512, p->sgu_ln_b + li * 512, p->sgu_w + (size_t)li * 4 * 128 * 128, p->sgu_b + li * 4 * 128, idx, tq);
;                     else { const int u = idx - 128, jq = 7 - (u >> 6), bh = u & 63; mx::sb_unit(lds, PROJ, MIX, bh >> 3, bh & 7, jq, tq); }
.Lq_join:
	s_waitcnt vmcnt(0)
	v_readfirstlane_b32 s2, v2
	v_readlane_b32 s3, v255, 10
	v_mov_b32_e32 v2, s76
	s_add_i32 s2, s2, s3
	v_add_u32_e32 v0, s2, v0
	ds_write_b32 v2, v0
.LBB0_326:
	s_or_b64 exec, exec, s[0:1]
	s_mov_b32 s98, 0
	v_mov_b32_e32 v0, s76
	s_waitcnt vmcnt(0) lgkmcnt(0)
	s_barrier
	ds_read_b32 v0, v0
	s_mov_b64 s[0:1], -1
	s_waitcnt lgkmcnt(0)
	s_barrier
	v_readfirstlane_b32 s24, v0
	s_cmp_ge_i32 s24, s13
	s_cbranch_scc1 .LBB0_321
	s_and_b64 vcc, exec, s[92:93]
	v_mov_b32 v200, v236
	s_cbranch_vccz .LBB0_367
	s_cmpk_gt_i32 s24, 0x7f
	s_cbranch_scc0 .LBB0_357
	s_add_i32 s0, s24, 0xffffff80
	s_lshr_b32 s4, s0, 6
	v_readfirstlane_b32 s0, v200
	s_ashr_i32 s5, s0, 6
	s_lshl_b32 s0, s24, 8
	s_sub_i32 s6, 7, s4
	s_and_b32 s0, s0, 0x3800
	s_lshl_b32 s7, s6, 8
	s_mul_i32 s1, s0, 0x1400
	s_add_u32 s2, s84, s1
	s_addc_u32 s3, s85, 0
	s_lshl_b32 s1, s24, 6
	s_and_b32 s10, s1, 0x1c0
	s_ashr_i32 s1, s7, 31
	s_add_u32 s0, s7, s0
	v_and_b32_e32 v5, 31, v200
	s_addc_u32 s1, s1, 0
	s_lshl_b32 s8, s5, 5
	s_ashr_i32 s9, s8, 31
	v_or_b32_e32 v2, s0, v5
	v_mov_b32_e32 v3, s1
	v_lshl_add_u64 v[202:203], v[2:3], 0, s[8:9]
	v_mov_b64_e32 v[2:3], s[84:85]
	v_mad_u64_u32 v[2:3], s[0:1], v202, s40, v[2:3]
	s_lshl_b32 s82, s10, 1
	v_bfe_u32 v4, v200, 5, 1
	v_mad_i32_i24 v3, v203, s40, v3
	s_add_u32 s0, s2, s82
	v_lshl_add_u64 v[2:3], v[2:3], 0, s[82:83]
	v_lshlrev_b32_e32 v0, 4, v4
	s_addc_u32 s1, s3, 0
	v_lshl_add_u64 v[2:3], v[2:3], 0, v[0:1]
	s_add_u32 s2, s0, 0x1000
	global_load_dwordx4 v[176:179], v[2:3], off offset:2048
	global_load_dwordx4 v[180:183], v[2:3], off offset:2080
	global_load_dwordx4 v[184:187], v[2:3], off offset:2112
	global_load_dwordx4 v[188:191], v[2:3], off offset:2144
	s_addc_u32 s3, s1, 0
	s_or_b32 s9, s7, 0xc0
	v_ashrrev_i32_e32 v201, 3, v200
	v_lshlrev_b32_e32 v2, 3, v200
	v_add_u32_e32 v12, s9, v201
	v_mov_b64_e32 v[6:7], s[0:1]
	v_and_b32_e32 v2, 56, v2
	v_mad_i64_i32 v[8:9], s[10:11], v12, s40, v[6:7]
	v_lshlrev_b32_e32 v2, 1, v2
	v_mov_b32_e32 v3, v1
	v_lshl_add_u64 v[8:9], v[8:9], 0, v[2:3]
	v_mov_b64_e32 v[10:11], s[2:3]
	global_load_dwordx4 v[192:195], v[8:9], off offset:3072
	v_mad_i64_i32 v[8:9], s[10:11], v12, s40, v[10:11]
	v_lshl_add_u64 v[8:9], v[8:9], 0, v[2:3]
	global_load_dwordx4 v[196:199], v[8:9], off
	v_add_u32_e32 v8, s7, v201
	v_add_u32_e32 v12, 0x80, v8
	v_mad_i64_i32 v[6:7], s[10:11], v12, s40, v[6:7]
	v_lshl_add_u64 v[6:7], v[6:7], 0, v[2:3]
	v_mad_i64_i32 v[10:11], s[10:11], v12, s40, v[10:11]
	global_load_dwordx4 v[6:9], v[6:7], off offset:3072
	v_lshl_add_u64 v[10:11], v[10:11], 0, v[2:3]
	global_load_dwordx4 v[10:13], v[10:11], off
	s_add_i32 s25, s8, s7
	s_or_b32 s92, s25, 30
	v_lshlrev_b32_e32 v14, 4, v200
	s_cmp_le_i32 s9, s92
	v_mul_lo_u32 v3, v201, s43
	v_and_b32_e32 v14, 0x70, v14
	s_cselect_b64 s[16:17], -1, 0
	v_add3_u32 v210, 0, v3, v14
	s_mov_b64 s[8:9], -1
	s_and_b64 vcc, exec, s[16:17]
	s_waitcnt vmcnt(3)
	ds_write_b128 v210, v[192:195]
	s_waitcnt vmcnt(2)
	ds_write_b128 v210, v[196:199] offset:27648
	s_waitcnt vmcnt(1)
	ds_write_b128 v210, v[6:9] offset:9216
	s_waitcnt vmcnt(0)
	ds_write_b128 v210, v[10:13] offset:36864
	s_waitcnt lgkmcnt(0)
	s_barrier
	s_cbranch_vccnz .LBB0_331
	v_lshlrev_b32_e32 v6, 4, v4
	s_mov_b64 s[8:9], 0

; __device__ __forceinline__ void conv_item(LAS unsigned char* lds, const bf16* PROJ, bf16* MIX, const float* cw, const float* cb, const float* lg, const float* lb, int item, int tid) {
;     ...
;     for (int q = 0; q < 4; ++q) { const int tk = 4 * wid + q; float v[8]; float s = 0.f;
; #pragma unroll
;         for (int i = 0; i < 8; ++i) { v[i] = cbuf[tk * 512 + lane + 64 * i]; s += v[i]; }
;         const float mean = wave_sum(s, lane) * (1.f / 512.f); float s2 = 0.f;
; #pragma unroll
;         for (int i = 0; i < 8; ++i) { const float d = v[i] - mean; s2 += d * d; }
;         const float rstd = 1.0f / sqrtf(wave_sum(s2, lane) * (1.f / 512.f) + 1e-5f);
;         if (lane == 0) { st[2 * tk] = mean; st[2 * tk + 1] = rstd; } }
; __global__ void __launch_bounds__(NTHREADS, 2) fwd_megakernel(Params p_) {
;     ...
;                 if (tid == 0) *qslot = __hip_atomic_fetch_add(qctr, 1u, __ATOMIC_RELAXED, __HIP_MEMORY_SCOPE_AGENT);
.LBB0_434:
	s_mov_b64 s[98:99], exec
	v_readlane_b32 s100, v255, 32
	v_readlane_b32 s101, v255, 33
	s_nop 0
	s_and_b64 exec, exec, s[100:101]
	s_cbranch_execz .Lpf_skip1
	v_readlane_b32 s100, v255, 18
	v_readlane_b32 s101, v255, 19
	v_mov_b32_e32 v237, 1
	s_nop 3
	global_atomic_add v237, v236, v237, s[100:101] sc0
.Lpf_skip1:
	s_mov_b64 exec, s[98:99]
	s_mov_b32 s98, 1
	s_or_b64 exec, exec, s[0:1]
	s_or_b32 s5, s4, 1
	v_lshl_add_u32 v10, s5, 11, v9
	s_waitcnt lgkmcnt(0)
	ds_read2st64_b32 v[12:13], v10 offset1:1
	ds_read2st64_b32 v[14:15], v10 offset0:2 offset1:3
	ds_read2st64_b32 v[16:17], v10 offset0:4 offset1:5
	ds_read2st64_b32 v[18:19], v10 offset0:6 offset1:7
	s_waitcnt lgkmcnt(3)
	v_add_f32_e32 v10, 0, v12
	v_add_f32_e32 v10, v10, v13
	s_waitcnt lgkmcnt(2)
	v_add_f32_e32 v10, v10, v14
	v_add_f32_e32 v10, v10, v15
	s_waitcnt lgkmcnt(1)
	v_add_f32_e32 v10, v10, v16
	v_add_f32_e32 v10, v10, v17
	s_waitcnt lgkmcnt(0)
	v_add_f32_e32 v10, v10, v18
	v_add_f32_e32 v10, v10, v19
	ds_bpermute_b32 v11, v8, v10
	s_waitcnt lgkmcnt(0)
	v_add_f32_e32 v10, v10, v11
	ds_bpermute_b32 v11, v7, v10
	s_waitcnt lgkmcnt(0)
	v_add_f32_e32 v10, v10, v11
	ds_bpermute_b32 v11, v6, v10
	s_waitcnt lgkmcnt(0)
	v_add_f32_e32 v10, v10, v11
	ds_bpermute_b32 v11, v5, v10
	s_waitcnt lgkmcnt(0)
	v_add_f32_e32 v10, v10, v11
	ds_bpermute_b32 v11, v4, v10
	s_waitcnt lgkmcnt(0)
	v_add_f32_e32 v10, v10, v11
	ds_bpermute_b32 v11, v0, v10
	s_waitcnt lgkmcnt(0)
	v_add_f32_e32 v10, v10, v11
	v_fmac_f32_e32 v13, 0xbb000000, v10
	v_fmamk_f32 v11, v10, 0xbb000000, v12
	v_mul_f32_e32 v13, v13, v13
	v_fmamk_f32 v12, v10, 0xbb000000, v14
	v_fmac_f32_e32 v13, v11, v11
	v_fmac_f32_e32 v15, 0xbb000000, v10
	v_fmac_f32_e32 v13, v12, v12
	v_fmamk_f32 v14, v10, 0xbb000000, v16
	v_fmac_f32_e32 v13, v15, v15
	v_fmac_f32_e32 v17, 0xbb000000, v10
	v_fmac_f32_e32 v13, v14, v14
	v_fmamk_f32 v16, v10, 0xbb000000, v18
	v_fmac_f32_e32 v13, v17, v17
	v_fmac_f32_e32 v13, v16, v16
	v_fmac_f32_e32 v19, 0xbb000000, v10
	v_fmac_f32_e32 v13, v19, v19
	ds_bpermute_b32 v11, v8, v13
	s_waitcnt lgkmcnt(0)
	v_add_f32_e32 v11, v13, v11
	ds_bpermute_b32 v12, v7, v11
	s_waitcnt lgkmcnt(0)
	v_add_f32_e32 v11, v11, v12
	ds_bpermute_b32 v12, v6, v11
	s_waitcnt lgkmcnt(0)
	v_add_f32_e32 v11, v11, v12
	ds_bpermute_b32 v12, v5, v11
	s_waitcnt lgkmcnt(0)
	v_add_f32_e32 v11, v11, v12
	ds_bpermute_b32 v12, v4, v11
	s_waitcnt lgkmcnt(0)
	v_add_f32_e32 v11, v11, v12
	ds_bpermute_b32 v12, v0, v11
	s_and_saveexec_b64 s[0:1], s[8:9]
	v_readlane_b32 s18, v255, 32
	v_readlane_b32 s19, v255, 33
	s_cbranch_execz .LBB0_436
	s_waitcnt lgkmcnt(0)
	v_add_f32_e32 v11, v11, v12
	v_fmamk_f32 v11, v11, 0x3b000000, v232
	v_mul_f32_e32 v12, 0x4f800000, v11
	v_cmp_gt_f32_e32 vcc, s80, v11
	s_lshl_b32 s5, s5, 3
	s_add_i32 s5, s5, 0
	v_cndmask_b32_e32 v11, v11, v12, vcc
	v_sqrt_f32_e32 v12, v11
	s_add_i32 s5, s5, 0x10000
	v_mul_f32_e32 v10, 0x3b000000, v10
	v_add_u32_e32 v13, -1, v12
	v_fma_f32 v15, -v13, v12, v11
	v_add_u32_e32 v14, 1, v12
	v_cmp_ge_f32_e64 s[10:11], 0, v15
	s_nop 1
	v_cndmask_b32_e64 v13, v12, v13, s[10:11]
	v_fma_f32 v12, -v14, v12, v11
	v_cmp_lt_f32_e64 s[10:11], 0, v12
	s_nop 1
	v_cndmask_b32_e64 v12, v13, v14, s[10:11]
	v_mul_f32_e32 v13, 0x37800000, v12
	v_cndmask_b32_e32 v12, v12, v13, vcc
	v_cmp_class_f32_e32 vcc, v11, v231
	s_nop 1
	v_cndmask_b32_e32 v11, v12, v11, vcc
	v_div_scale_f32 v12, s[6:7], v11, v11, 1.0
	v_rcp_f32_e32 v13, v12
	s_nop 0
	v_fma_f32 v14, -v12, v13, 1.0
	v_fmac_f32_e32 v13, v14, v13
	v_div_scale_f32 v14, vcc, 1.0, v11, 1.0
	v_mul_f32_e32 v15, v14, v13
	v_fma_f32 v16, -v12, v15, v14
	v_fmac_f32_e32 v15, v16, v13
	v_fma_f32 v12, -v12, v15, v14
	v_div_fmas_f32 v12, v12, v13, v15
	v_div_fixup_f32 v11, v12, v11, 1.0
	v_mov_b32_e32 v12, s5
	ds_write_b64 v12, v[10:11]

; __device__ __forceinline__ float fexp2(float x) { return __builtin_amdgcn_exp2f(x); }
; __device__ __forceinline__ float shx(float v, int o, int lane) { return __builtin_bit_cast(float, __builtin_amdgcn_ds_bpermute((lane ^ o) << 2, __builtin_bit_cast(int, v))); }
; __device__ __forceinline__ int crow(int r, int hi) { return (r & 3) + 8 * (r >> 2) + 4 * hi; }
; template <bool DIAG> __device__ __forceinline__ void moba_softmax(f32x16& p0, f32x16& p1, int t, int qrel, int hi, int lane, bool mysel, float C, float& mrun, float& lrun, f32x16 (&o)[2]) {
;     float bias = 0.f;
;     if (DIAG) {
; #pragma unroll
;         for (int r = 0; r < 16; ++r) { const int kv = 64 * t + crow(r, hi); p0[r] = kv <= qrel ? p0[r] : -INFINITY; p1[r] = kv + 32 <= qrel ? p1[r] : -INFINITY; }
;     } else bias = mysel ? 0.f : -INFINITY;
;     float rm = fmaxf(p0[0], p1[0]);
; #pragma unroll
;     for (int r = 1; r < 16; ++r) rm = fmaxf(rm, fmaxf(p0[r], p1[r]));
;     rm = fmaxf(rm, shx(rm, 32, lane));
;     const float mnew = fmaxf(mrun, rm * C + bias); const float alpha = fexp2(mrun - mnew);
; #pragma unroll
;     for (int r = 0; r < 16; ++r) { o[0][r] *= alpha; o[1][r] *= alpha; }
;     mrun = mnew; const float nb = bias - mnew; float rs = 0.f;
; #pragma unroll
;     for (int r = 0; r < 16; ++r) { p0[r] = fexp2(__builtin_fmaf(p0[r], C, nb)); p1[r] = fexp2(__builtin_fmaf(p1[r], C, nb)); rs += p0[r] + p1[r]; }
;     lrun = lrun * alpha + rs;
.Lpf_skip0:
	s_mov_b64 exec, s[98:99]
	s_mov_b32 s98, 1
	s_cmp_ge_u32 s0, s6
	s_cbranch_scc1 .LBB0_489
	s_cmp_lg_u32 s16, 0
	v_max_f32_e32 v196, v213, v213
	s_cbranch_scc0 .LBB0_493
	s_add_i32 s0, s10, 0
	v_add3_u32 v0, s0, v211, v168
	ds_read_b128 v[70:73], v0 offset:4608
	s_add_i32 s0, s16, -2
	s_lshr_b32 s0, s0, 2
	ds_read_b128 v[66:69], v0
	ds_read_b128 v[106:109], v0 offset:32
	ds_read_b128 v[74:77], v0 offset:4640
	ds_read_b128 v[102:105], v0 offset:64
	ds_read_b128 v[78:81], v0 offset:4672
	ds_read_b128 v[98:101], v0 offset:96
	ds_read_b128 v[110:113], v0 offset:4704
	v_bfe_u32 v0, v209, s0, 1
	v_cmp_eq_u32_e32 vcc, 0, v0
	s_waitcnt lgkmcnt(7)
	v_mfma_f32_32x32x16_bf16 v[82:97], v[70:73], v[142:145], 0
	v_max_f32_e32 v70, v51, v51
	v_max_f32_e32 v71, v35, v35
	v_max_f32_e32 v72, v52, v52
	v_max_f32_e32 v73, v36, v36
	v_max_f32_e32 v0, v71, v70
	v_max_f32_e32 v70, v73, v72
	v_max3_f32 v0, v34, v50, v0
	s_waitcnt lgkmcnt(4)
	v_mfma_f32_32x32x16_bf16 v[82:97], v[74:77], v[138:141], v[82:97]
	v_max_f32_e32 v74, v53, v53
	v_max_f32_e32 v75, v37, v37
	v_max_f32_e32 v71, v75, v74
	v_max_f32_e32 v76, v54, v54
	v_max_f32_e32 v77, v38, v38
	v_max3_f32 v0, v0, v70, v71
	s_add_i32 s0, s4, 0
	s_waitcnt lgkmcnt(2)
	v_mfma_f32_32x32x16_bf16 v[82:97], v[78:81], v[134:137], v[82:97]
	v_max_f32_e32 v78, v55, v55
	v_max_f32_e32 v79, v39, v39
	s_waitcnt lgkmcnt(0)
	v_mfma_f32_32x32x16_bf16 v[82:97], v[110:113], v[130:133], v[82:97]
	v_max_f32_e32 v110, v77, v76
	v_max_f32_e32 v111, v79, v78
	v_mfma_f32_32x32x16_bf16 v[66:81], v[66:69], v[142:145], 0
	v_mfma_f32_32x32x16_bf16 v[66:81], v[106:109], v[138:141], v[66:81]
	v_mfma_f32_32x32x16_bf16 v[66:81], v[102:105], v[134:137], v[66:81]
	v_mfma_f32_32x32x16_bf16 v[66:81], v[98:101], v[130:133], v[66:81]
	v_max_f32_e32 v112, v56, v56
	v_max_f32_e32 v113, v40, v40
	v_max3_f32 v0, v0, v110, v111
	v_max_f32_e32 v110, v113, v112
	v_max_f32_e32 v111, v57, v57
	v_max_f32_e32 v112, v41, v41
	v_max_f32_e32 v111, v112, v111
	v_max3_f32 v0, v0, v110, v111
	v_max_f32_e32 v110, v58, v58
	v_max_f32_e32 v111, v42, v42
	v_max_f32_e32 v110, v111, v110
	v_max_f32_e32 v111, v59, v59
	v_max_f32_e32 v112, v43, v43
	v_max_f32_e32 v111, v112, v111
	v_max3_f32 v0, v0, v110, v111
	v_max_f32_e32 v110, v60, v60
	v_max_f32_e32 v111, v44, v44
	v_max_f32_e32 v110, v111, v110
	v_max_f32_e32 v111, v61, v61
	v_max_f32_e32 v112, v45, v45
	v_max_f32_e32 v106, v112, v111
	v_max3_f32 v0, v0, v110, v106
	v_max_f32_e32 v106, v62, v62
	v_max_f32_e32 v107, v46, v46
	v_max_f32_e32 v106, v107, v106
	v_max_f32_e32 v107, v63, v63
	v_max_f32_e32 v108, v47, v47
	v_max_f32_e32 v107, v108, v107
	v_max3_f32 v0, v0, v106, v107
	v_max_f32_e32 v106, v64, v64
	v_max_f32_e32 v107, v48, v48
	v_max_f32_e32 v106, v107, v106
	v_max_f32_e32 v107, v65, v65
	v_max_f32_e32 v108, v49, v49
	v_max_f32_e32 v107, v108, v107
	v_max3_f32 v0, v0, v106, v107
	ds_bpermute_b32 v106, v169, v0
	v_cndmask_b32_e32 v107, 0, v235, vcc
	s_waitcnt lgkmcnt(0)
	v_max_f32_e32 v106, v106, v106
	v_max_f32_e32 v0, v0, v106
	v_fmamk_f32 v0, v0, 0x3e38aa3b, v107
	v_max_f32_e32 v177, v196, v0
	v_sub_f32_e32 v104, v213, v177
	v_exp_f32_e32 v176, v104
	s_nop 0
	v_pk_mul_f32 v[118:119], v[6:7], v[176:177] op_sel_hi:[1,0]
	v_pk_mul_f32 v[112:113], v[32:33], v[176:177] op_sel_hi:[1,0]
	v_sub_f32_e32 v102, v107, v177
	v_fmamk_f32 v101, v41, 0x3e38aa3b, v102
	v_exp_f32_e32 v178, v101
	v_fmamk_f32 v101, v43, 0x3e38aa3b, v102
	v_exp_f32_e32 v180, v101
	v_fmamk_f32 v101, v59, 0x3e38aa3b, v102
	v_exp_f32_e32 v186, v101
	v_fmamk_f32 v101, v45, 0x3e38aa3b, v102
	v_exp_f32_e32 v184, v101
	v_fmamk_f32 v101, v61, 0x3e38aa3b, v102
	v_fmamk_f32 v105, v35, 0x3e38aa3b, v102
	v_exp_f32_e32 v170, v105
	v_fmamk_f32 v105, v60, 0x3e38aa3b, v102
	v_exp_f32_e32 v105, v105
	v_exp_f32_e32 v192, v101
	s_waitcnt vmcnt(1)
	v_cvt_pk_bf16_f32 v147, v105, v192
	v_fmamk_f32 v104, v44, 0x3e38aa3b, v102
	v_exp_f32_e32 v104, v104
	s_waitcnt vmcnt(0)
; #define LAS __attribute__((address_space(3)))
; __device__ __forceinline__ unsigned cvtpk(float lo, float hi) { f32x2_t v = {lo, hi}; bf16x2_t b = __builtin_convertvector(v, bf16x2_t); return __builtin_bit_cast(unsigned, b); }
; __device__ __forceinline__ float fexp2(float x) { return __builtin_amdgcn_exp2f(x); }
; #define MFMA32(a, b, c) __builtin_amdgcn_mfma_f32_32x32x16_bf16((a), (b), (c), 0, 0, 0)
; __device__ __forceinline__ void pv_tile(LAS const unsigned char* Vb, int lane, const f32x16& p0, const f32x16& p1, f32x16 (&o)[2]) {
;     const int i = lane & 15, q4 = i >> 2, pp = i & 3, g1 = (lane >> 4) & 1, hi = lane >> 5;
;     LAS const unsigned char* vb = Vb + (4 * hi + q4) * KP + g1 * 32 + pp * 8;
; #pragma unroll
;     for (int sub = 0; sub < 2; ++sub)
; #pragma unroll
;         for (int s = 0; s < 2; ++s) {
;             u32x4 pk;
;             if (sub == 0) { pk.x = cvtpk(p0[8 * s], p0[8 * s + 1]); pk.y = cvtpk(p0[8 * s + 2], p0[8 * s + 3]); pk.z = cvtpk(p0[8 * s + 4], p0[8 * s + 5]); pk.w = cvtpk(p0[8 * s + 6], p0[8 * s + 7]); }
;             else          { pk.x = cvtpk(p1[8 * s], p1[8 * s + 1]); pk.y = cvtpk(p1[8 * s + 2], p1[8 * s + 3]); pk.z = cvtpk(p1[8 * s + 4], p1[8 * s + 5]); pk.w = cvtpk(p1[8 * s + 6], p1[8 * s + 7]); }
;             const bf16x8 pb = __builtin_bit_cast(bf16x8, pk);
; #pragma unroll
;             for (int d0 = 0; d0 < 2; ++d0) {
;                 const s16x4 lo = vtr(vb + (32 * sub + 16 * s) * KP + d0 * 64);
;                 const s16x4 hh = vtr(vb + (32 * sub + 16 * s + 8) * KP + d0 * 64);
;                 const bf16x8 va = {lo[0], lo[1], lo[2], lo[3], hh[0], hh[1], hh[2], hh[3]};
;                 o[d0] = MFMA32(va, pb, o[d0]);
;             }
;         }
; template <bool DIAG> __device__ __forceinline__ void moba_softmax(f32x16& p0, f32x16& p1, int t, int qrel, int hi, int lane, bool mysel, float C, float& mrun, float& lrun, f32x16 (&o)[2]) {
;     ...
;     mrun = mnew; const float nb = bias - mnew; float rs = 0.f;
; #pragma unroll
;     for (int r = 0; r < 16; ++r) { p0[r] = fexp2(__builtin_fmaf(p0[r], C, nb)); p1[r] = fexp2(__builtin_fmaf(p1[r], C, nb)); rs += p0[r] + p1[r]; }
;     lrun = lrun * alpha + rs;
	v_cvt_pk_bf16_f32 v151, v104, v184
	v_add_f32_e32 v185, v104, v105
	v_pk_mul_f32 v[104:105], v[24:25], v[176:177] op_sel_hi:[1,0]
	v_fmamk_f32 v110, v40, 0x3e38aa3b, v102
	v_exp_f32_e32 v98, v110
	s_nop 0
	v_cvt_pk_bf16_f32 v161, v98, v178
	v_fmamk_f32 v99, v42, 0x3e38aa3b, v102
	v_exp_f32_e32 v99, v99
	s_nop 0
	v_cvt_pk_bf16_f32 v150, v99, v180
	v_fmamk_f32 v100, v58, 0x3e38aa3b, v102
	v_exp_f32_e32 v100, v100
	s_nop 0
	v_add_f32_e32 v181, v99, v100
	v_fmamk_f32 v111, v56, 0x3e38aa3b, v102
	v_exp_f32_e32 v199, v111
	s_nop 0
	v_add_f32_e32 v179, v98, v199
	v_pk_mul_f32 v[98:99], v[18:19], v[176:177] op_sel_hi:[1,0]
	v_fmamk_f32 v107, v52, 0x3e38aa3b, v102
	v_exp_f32_e32 v191, v107
	v_fmamk_f32 v107, v38, 0x3e38aa3b, v102
	v_fmamk_f32 v109, v39, 0x3e38aa3b, v102
	v_exp_f32_e32 v107, v107
	v_exp_f32_e32 v172, v109
	s_nop 0
	v_cvt_pk_bf16_f32 v160, v107, v172
	v_fmamk_f32 v108, v54, 0x3e38aa3b, v102
	v_fmamk_f32 v106, v36, 0x3e38aa3b, v102
	v_exp_f32_e32 v193, v108
	v_fmamk_f32 v108, v37, 0x3e38aa3b, v102
	v_exp_f32_e32 v106, v106
	v_exp_f32_e32 v174, v108
	s_nop 0
	v_cvt_pk_bf16_f32 v159, v106, v174
	v_add_f32_e32 v175, v106, v191
	v_add_f32_e32 v173, v107, v193
	v_pk_mul_f32 v[106:107], v[26:27], v[176:177] op_sel_hi:[1,0]
	v_fmamk_f32 v101, v47, 0x3e38aa3b, v102
	v_exp_f32_e32 v182, v101
	v_fmamk_f32 v101, v63, 0x3e38aa3b, v102
	v_fmamk_f32 v109, v62, 0x3e38aa3b, v102
	v_exp_f32_e32 v109, v109
	v_exp_f32_e32 v190, v101
	s_nop 0
	v_cvt_pk_bf16_f32 v148, v109, v190
	v_fmamk_f32 v108, v46, 0x3e38aa3b, v102
	v_exp_f32_e32 v108, v108
	s_nop 0
	v_cvt_pk_bf16_f32 v152, v108, v182
	v_add_f32_e32 v183, v108, v109
	v_pk_mul_f32 v[108:109], v[28:29], v[176:177] op_sel_hi:[1,0]
	v_fmamk_f32 v101, v49, 0x3e38aa3b, v102
	v_exp_f32_e32 v188, v101
	v_add_u32_e32 v101, s0, v205
	v_add3_u32 v198, v101, v206, v207
	ds_read_b64_tr_b16 v[114:115], v198 offset:27648
	ds_read_b64_tr_b16 v[116:117], v198 offset:28800
	v_cvt_pk_bf16_f32 v146, v100, v186
	v_pk_mul_f32 v[100:101], v[20:21], v[176:177] op_sel_hi:[1,0]
	v_fmamk_f32 v111, v64, 0x3e38aa3b, v102
	v_fmamk_f32 v200, v57, 0x3e38aa3b, v102
	v_fmamk_f32 v110, v48, 0x3e38aa3b, v102
	v_fmamk_f32 v0, v34, 0x3e38aa3b, v102
	v_exp_f32_e32 v103, v0
	v_fmamk_f32 v0, v50, 0x3e38aa3b, v102
	v_exp_f32_e32 v187, v0
	v_fmamk_f32 v0, v51, 0x3e38aa3b, v102
	v_fmamk_f32 v195, v53, 0x3e38aa3b, v102
	v_fmamk_f32 v197, v55, 0x3e38aa3b, v102
	v_fmac_f32_e32 v102, 0x3e38aa3b, v65
	v_exp_f32_e32 v110, v110
	v_exp_f32_e32 v111, v111
	v_exp_f32_e32 v194, v102
	ds_read_b64_tr_b16 v[154:155], v198 offset:29952
	ds_read_b64_tr_b16 v[156:157], v198 offset:31104
	ds_read_b64_tr_b16 v[162:163], v198 offset:27712
	v_cvt_pk_bf16_f32 v149, v111, v194
	v_cvt_pk_bf16_f32 v158, v103, v170
	v_add_f32_e32 v171, v103, v187
	v_pk_mul_f32 v[102:103], v[22:23], v[176:177] op_sel_hi:[1,0]
	v_add_f32_e32 v189, v110, v111
	v_cvt_pk_bf16_f32 v153, v110, v188
	v_pk_mul_f32 v[110:111], v[30:31], v[176:177] op_sel_hi:[1,0]
	ds_read_b64_tr_b16 v[164:165], v198 offset:28864
	v_exp_f32_e32 v0, v0
	s_waitcnt lgkmcnt(4)
	v_mfma_f32_32x32x16_bf16 v[98:113], v[114:117], v[158:161], v[98:113]
	v_mul_f32_e64 v116, v4, v176
	v_mul_f32_e64 v117, v5, v176
	v_mul_f32_e64 v114, v2, v176
	v_mul_f32_e64 v115, v3, v176
	v_mul_f32_e64 v128, v16, v176
	v_mul_f32_e64 v129, v17, v176
	v_pk_mul_f32 v[126:127], v[14:15], v[176:177] op_sel_hi:[1,0]
	v_pk_mul_f32 v[124:125], v[12:13], v[176:177] op_sel_hi:[1,0]
	v_pk_mul_f32 v[122:123], v[10:11], v[176:177] op_sel_hi:[1,0]
	v_pk_mul_f32 v[120:121], v[8:9], v[176:177] op_sel_hi:[1,0]
	s_waitcnt lgkmcnt(2)
	v_mfma_f32_32x32x16_bf16 v[98:113], v[154:157], v[150:153], v[98:113]
	ds_read_b64_tr_b16 v[154:155], v198 offset:32256
	ds_read_b64_tr_b16 v[156:157], v198 offset:33408
	v_exp_f32_e32 v214, v195
	v_exp_f32_e32 v216, v197
	v_exp_f32_e32 v218, v200
	v_pk_add_f32 v[170:171], v[170:171], v[0:1]
	ds_read_b64_tr_b16 v[200:201], v198 offset:32320
	s_waitcnt lgkmcnt(3)
	v_mfma_f32_32x32x16_bf16 v[114:129], v[162:165], v[158:161], v[114:129]
	ds_read_b64_tr_b16 v[158:159], v198 offset:30016
	ds_read_b64_tr_b16 v[160:161], v198 offset:31168
	v_pk_add_f32 v[170:171], v[170:171], v[170:171] op_sel_hi:[0,1]
	v_cvt_pk_bf16_f32 v162, v187, v0
	v_cvt_pk_bf16_f32 v163, v191, v214
	v_cvt_pk_bf16_f32 v164, v193, v216
	v_cvt_pk_bf16_f32 v165, v199, v218
	v_mov_b32_e32 v215, v171
	ds_read_b64_tr_b16 v[202:203], v198 offset:33472
	s_waitcnt lgkmcnt(4)
	v_mfma_f32_32x32x16_bf16 v[98:113], v[154:157], v[162:165], v[98:113]
	v_add_f32_e64 v154, v174, v214
	v_add_f32_e64 v155, v175, v215
	v_pk_add_f32 v[154:155], v[154:155], v[154:155] op_sel_hi:[0,1]
	v_mov_b32_e32 v217, v155
	v_pk_add_f32 v[154:155], v[172:173], v[216:217]
	s_nop 0
	v_pk_add_f32 v[154:155], v[154:155], v[154:155] op_sel_hi:[0,1]
	s_waitcnt lgkmcnt(1)
	v_mfma_f32_32x32x16_bf16 v[114:129], v[158:161], v[150:153], v[114:129]
	v_mov_b32_e32 v219, v155
	ds_read_b64_tr_b16 v[150:151], v198 offset:34560
	ds_read_b64_tr_b16 v[152:153], v198 offset:35712
	v_add_f32_e64 v154, v178, v218
	v_add_f32_e64 v155, v179, v219
	ds_read_b64_tr_b16 v[158:159], v198 offset:34624
	v_pk_add_f32 v[154:155], v[154:155], v[154:155] op_sel_hi:[0,1]
	v_mov_b32_e32 v187, v155
	v_pk_add_f32 v[154:155], v[180:181], v[186:187]
	ds_read_b64_tr_b16 v[160:161], v198 offset:35776
	v_pk_add_f32 v[154:155], v[154:155], v[154:155] op_sel_hi:[0,1]
	v_mov_b32_e32 v193, v155
	s_waitcnt lgkmcnt(4)
	v_mfma_f32_32x32x16_bf16 v[114:129], v[200:203], v[162:165], v[114:129]
	v_add_f32_e64 v154, v184, v192
	v_add_f32_e64 v155, v185, v193
	v_pk_add_f32 v[154:155], v[154:155], v[154:155] op_sel_hi:[0,1]
	v_mov_b32_e32 v191, v155
	s_waitcnt lgkmcnt(2)
	v_mfma_f32_32x32x16_bf16 v[98:113], v[150:153], v[146:149], v[98:113]
	v_add_f32_e64 v150, v182, v190
	v_add_f32_e64 v151, v183, v191
	v_pk_add_f32 v[150:151], v[150:151], v[150:151] op_sel_hi:[0,1]
	v_mov_b32_e32 v195, v151
	v_pk_add_f32 v[150:151], v[188:189], v[194:195]
	s_nop 0
	v_add_f32_e32 v0, v150, v151
	v_fmac_f32_e32 v0, v210, v176
	s_waitcnt lgkmcnt(0)
	v_mfma_f32_32x32x16_bf16 v[114:129], v[158:161], v[146:149], v[114:129]
	s_cbranch_execnz .LBB0_488
